# P0 split order by wave parity (odd waves RMSNorm first) + nt once-read loads
# baseline (speedup 1.0000x reference)
; __device__ __forceinline__ void p0_prologue(const Frame& F, const Ptrs& P) {
;     const int gw = F.bid * NWAVES + F.wave, NGW = F.G * NWAVES;
;     convert_weights<0>(F, gw, NGW);
;     for (int m = gw; m < M; m += NGW) { const float* xr = (m < MP) ? P_x_prompt + (size_t)m * DM : P_x_sample + (size_t)(m - MP) * DM; rms_row_to_bf16(xr, P_mix_nw, P_XN + (size_t)m * DM, F.lane); }
.Lp0_conv_entry:
	s_lshl_b32 s4, s2, 3
	s_add_i32 s8, s94, s4
	s_lshl_b32 s10, s3, 3
	s_cmp_lg_u32 s98, 0
	s_cbranch_scc1 .Lp0_conv_go
	s_bitcmp0_b32 s94, 0
	s_cbranch_scc1 .Lp0_conv_go
	s_mov_b32 s98, 1
	s_branch .LBB0_13
